# phase 15 K/V staging: 16 row loads issued up front with counted waits instead of 8 serialized pairs
# baseline (speedup 1.0000x reference)
.LBB0_765:
	s_bfe_u32 s6, s53, 0x70004
	s_lshl_b32 s8, s6, 7
	v_mov_b32_e32 v85, v205
	s_add_i32 s10, s8, 0xffffff80
	v_and_b32_e32 v10, 7, v85
	v_ashrrev_i32_e32 v1, 3, v85
	s_lshl_b32 s4, s53, 3
	v_lshlrev_b32_e32 v2, 3, v10
	v_add_u32_e32 v11, s10, v1
	s_and_b32 s7, s38, 0xffffc000
	s_and_b32 s9, s4, 64
	v_cmp_lt_i32_e32 vcc, -1, v11
	v_mov_b32_e32 v0, 0
	v_lshlrev_b32_e32 v80, 1, v2
	v_mov_b32_e32 v6, 0
	v_mov_b32_e32 v7, 0
	v_mov_b32_e32 v8, 0
	v_mov_b32_e32 v9, 0
	v_mov_b32_e32 v2, 0
	v_mov_b32_e32 v3, 0
	v_mov_b32_e32 v4, 0
	v_mov_b32_e32 v5, 0
	s_barrier
	v_lshlrev_b32_e32 v12, 4, v10
	v_mad_u32_u24 v13, v10, s41, v12
	s_lshl_b32 s16, s9, 1
	v_mov_b64_e32 v[136:137], s[44:45]
	v_lshl_add_u64 v[136:137], v[136:137], 0, s[16:17]
	v_lshl_add_u64 v[136:137], v[136:137], 0, v[80:81]
	v_mov_b32_e32 v138, v1
	v_mov_b32_e32 v146, 0
	v_mov_b32_e32 v147, 0
	v_mov_b32_e32 v148, 0
	v_mov_b32_e32 v149, 0
	v_mov_b32_e32 v150, 0
	v_mov_b32_e32 v151, 0
	v_mov_b32_e32 v152, 0
	v_mov_b32_e32 v153, 0
	v_add_u32_e32 v204, s10, v138
	v_cmp_lt_i32_e32 vcc, -1, v204
	v_add_u32_e32 v206, s7, v204
	s_and_saveexec_b64 s[4:5], vcc
	v_mad_i64_i32 v[202:203], s[12:13], v206, s40, v[136:137]
	global_load_dwordx4 v[146:149], v[202:203], off offset:2048
	global_load_dwordx4 v[150:153], v[202:203], off offset:2304
	s_or_b64 exec, exec, s[4:5]
	v_add_u32_e32 v139, 32, v1
	v_mov_b32_e32 v154, 0
	v_mov_b32_e32 v155, 0
	v_mov_b32_e32 v156, 0
	v_mov_b32_e32 v157, 0
	v_mov_b32_e32 v158, 0
	v_mov_b32_e32 v159, 0
	v_mov_b32_e32 v160, 0
	v_mov_b32_e32 v161, 0
	v_add_u32_e32 v204, s10, v139
	v_cmp_lt_i32_e32 vcc, -1, v204
	v_add_u32_e32 v206, s7, v204
	s_and_saveexec_b64 s[4:5], vcc
	v_mad_i64_i32 v[202:203], s[12:13], v206, s40, v[136:137]
	global_load_dwordx4 v[154:157], v[202:203], off offset:2048
	global_load_dwordx4 v[158:161], v[202:203], off offset:2304
	s_or_b64 exec, exec, s[4:5]
	v_add_u32_e32 v140, 64, v1
	v_mov_b32_e32 v162, 0
	v_mov_b32_e32 v163, 0
	v_mov_b32_e32 v164, 0
	v_mov_b32_e32 v165, 0
	v_mov_b32_e32 v166, 0
	v_mov_b32_e32 v167, 0
	v_mov_b32_e32 v168, 0
	v_mov_b32_e32 v169, 0
	v_add_u32_e32 v204, s10, v140
	v_cmp_lt_i32_e32 vcc, -1, v204
	v_add_u32_e32 v206, s7, v204
	s_and_saveexec_b64 s[4:5], vcc
	v_mad_i64_i32 v[202:203], s[12:13], v206, s40, v[136:137]
	global_load_dwordx4 v[162:165], v[202:203], off offset:2048
	global_load_dwordx4 v[166:169], v[202:203], off offset:2304
	s_or_b64 exec, exec, s[4:5]
	v_add_u32_e32 v141, 96, v1
	v_mov_b32_e32 v170, 0
	v_mov_b32_e32 v171, 0
	v_mov_b32_e32 v172, 0
	v_mov_b32_e32 v173, 0
	v_mov_b32_e32 v174, 0
	v_mov_b32_e32 v175, 0
	v_mov_b32_e32 v176, 0
	v_mov_b32_e32 v177, 0
	v_add_u32_e32 v204, s10, v141
	v_cmp_lt_i32_e32 vcc, -1, v204
	v_add_u32_e32 v206, s7, v204
	s_and_saveexec_b64 s[4:5], vcc
	v_mad_i64_i32 v[202:203], s[12:13], v206, s40, v[136:137]
	global_load_dwordx4 v[170:173], v[202:203], off offset:2048
	global_load_dwordx4 v[174:177], v[202:203], off offset:2304
	s_or_b64 exec, exec, s[4:5]
	v_add_u32_e32 v142, 128, v1
	v_mov_b32_e32 v178, 0
	v_mov_b32_e32 v179, 0
	v_mov_b32_e32 v180, 0
	v_mov_b32_e32 v181, 0
	v_mov_b32_e32 v182, 0
	v_mov_b32_e32 v183, 0
	v_mov_b32_e32 v184, 0
	v_mov_b32_e32 v185, 0
	v_add_u32_e32 v204, s10, v142
	v_cmp_lt_i32_e32 vcc, -1, v204
	v_add_u32_e32 v206, s7, v204
	s_and_saveexec_b64 s[4:5], vcc
	v_mad_i64_i32 v[202:203], s[12:13], v206, s40, v[136:137]
	global_load_dwordx4 v[178:181], v[202:203], off offset:2048
	global_load_dwordx4 v[182:185], v[202:203], off offset:2304
	s_or_b64 exec, exec, s[4:5]
	v_add_u32_e32 v143, 160, v1
	v_mov_b32_e32 v186, 0
	v_mov_b32_e32 v187, 0
	v_mov_b32_e32 v188, 0
	v_mov_b32_e32 v189, 0
	v_mov_b32_e32 v190, 0
	v_mov_b32_e32 v191, 0
	v_mov_b32_e32 v192, 0
	v_mov_b32_e32 v193, 0
	v_add_u32_e32 v204, s10, v143
	v_cmp_lt_i32_e32 vcc, -1, v204
	v_add_u32_e32 v206, s7, v204
	s_and_saveexec_b64 s[4:5], vcc
	v_mad_i64_i32 v[202:203], s[12:13], v206, s40, v[136:137]
	global_load_dwordx4 v[186:189], v[202:203], off offset:2048
	global_load_dwordx4 v[190:193], v[202:203], off offset:2304
	s_or_b64 exec, exec, s[4:5]
	v_add_u32_e32 v144, 192, v1
	v_mov_b32_e32 v194, 0
	v_mov_b32_e32 v195, 0
	v_mov_b32_e32 v196, 0
	v_mov_b32_e32 v197, 0
	v_mov_b32_e32 v198, 0
	v_mov_b32_e32 v199, 0
	v_mov_b32_e32 v200, 0
	v_mov_b32_e32 v201, 0
	v_add_u32_e32 v204, s10, v144
	v_cmp_lt_i32_e32 vcc, -1, v204
	v_add_u32_e32 v206, s7, v204
	s_and_saveexec_b64 s[4:5], vcc
	v_mad_i64_i32 v[202:203], s[12:13], v206, s40, v[136:137]
	global_load_dwordx4 v[194:197], v[202:203], off offset:2048
	global_load_dwordx4 v[198:201], v[202:203], off offset:2304
	s_or_b64 exec, exec, s[4:5]
	v_add_u32_e32 v8, 224, v1
	v_mov_b32_e32 v4, 0
	v_mov_b32_e32 v5, 0
	v_mov_b32_e32 v6, 0
	v_mov_b32_e32 v7, 0
	v_mov_b32_e32 v0, 0
	v_mov_b32_e32 v1, 0
	v_mov_b32_e32 v2, 0
	v_mov_b32_e32 v3, 0
	v_add_u32_e32 v204, s10, v8
	v_cmp_lt_i32_e32 vcc, -1, v204
	v_add_u32_e32 v206, s7, v204
	s_and_saveexec_b64 s[4:5], vcc
	v_mad_i64_i32 v[202:203], s[12:13], v206, s40, v[136:137]
	global_load_dwordx4 v[4:7], v[202:203], off offset:2048
	global_load_dwordx4 v[0:3], v[202:203], off offset:2304
	s_or_b64 exec, exec, s[4:5]
	v_mad_u32_u24 v10, v138, s50, v12
	v_lshl_add_u32 v208, v138, 1, v13
	s_waitcnt vmcnt(15)
	ds_write_b128 v10, v[146:149]
	s_waitcnt vmcnt(14)
	ds_write_b16 v208, v150 offset:36864
	ds_write_b16_d16_hi v208, v150 offset:37392
	ds_write_b16 v208, v151 offset:37920
	ds_write_b16_d16_hi v208, v151 offset:38448
	ds_write_b16 v208, v152 offset:38976
	ds_write_b16_d16_hi v208, v152 offset:39504
	ds_write_b16 v208, v153 offset:40032
	ds_write_b16_d16_hi v208, v153 offset:40560
	v_mad_u32_u24 v10, v139, s50, v12
	v_lshl_add_u32 v208, v139, 1, v13
	s_waitcnt vmcnt(13)
	ds_write_b128 v10, v[154:157]
	s_waitcnt vmcnt(12)
	ds_write_b16 v208, v158 offset:36864
	ds_write_b16_d16_hi v208, v158 offset:37392
	ds_write_b16 v208, v159 offset:37920
	ds_write_b16_d16_hi v208, v159 offset:38448
	ds_write_b16 v208, v160 offset:38976
	ds_write_b16_d16_hi v208, v160 offset:39504
	ds_write_b16 v208, v161 offset:40032
	ds_write_b16_d16_hi v208, v161 offset:40560
	v_mad_u32_u24 v10, v140, s50, v12
	v_lshl_add_u32 v208, v140, 1, v13
	s_waitcnt vmcnt(11)
	ds_write_b128 v10, v[162:165]
	s_waitcnt vmcnt(10)
	ds_write_b16 v208, v166 offset:36864
	ds_write_b16_d16_hi v208, v166 offset:37392
	ds_write_b16 v208, v167 offset:37920
	ds_write_b16_d16_hi v208, v167 offset:38448
	ds_write_b16 v208, v168 offset:38976
	ds_write_b16_d16_hi v208, v168 offset:39504
	ds_write_b16 v208, v169 offset:40032
	ds_write_b16_d16_hi v208, v169 offset:40560
	v_mad_u32_u24 v10, v141, s50, v12
	v_lshl_add_u32 v208, v141, 1, v13
	s_waitcnt vmcnt(9)
	ds_write_b128 v10, v[170:173]
	s_waitcnt vmcnt(8)
	ds_write_b16 v208, v174 offset:36864
	ds_write_b16_d16_hi v208, v174 offset:37392
	ds_write_b16 v208, v175 offset:37920
	ds_write_b16_d16_hi v208, v175 offset:38448
	ds_write_b16 v208, v176 offset:38976
	ds_write_b16_d16_hi v208, v176 offset:39504
	ds_write_b16 v208, v177 offset:40032
	ds_write_b16_d16_hi v208, v177 offset:40560
	v_mad_u32_u24 v10, v142, s50, v12
	v_lshl_add_u32 v208, v142, 1, v13
	s_waitcnt vmcnt(7)
	ds_write_b128 v10, v[178:181]
	s_waitcnt vmcnt(6)
	ds_write_b16 v208, v182 offset:36864
	ds_write_b16_d16_hi v208, v182 offset:37392
	ds_write_b16 v208, v183 offset:37920
	ds_write_b16_d16_hi v208, v183 offset:38448
	ds_write_b16 v208, v184 offset:38976
	ds_write_b16_d16_hi v208, v184 offset:39504
	ds_write_b16 v208, v185 offset:40032
	ds_write_b16_d16_hi v208, v185 offset:40560
	v_mad_u32_u24 v10, v143, s50, v12
	v_lshl_add_u32 v208, v143, 1, v13
	s_waitcnt vmcnt(5)
	ds_write_b128 v10, v[186:189]
	s_waitcnt vmcnt(4)
	ds_write_b16 v208, v190 offset:36864
	ds_write_b16_d16_hi v208, v190 offset:37392
	ds_write_b16 v208, v191 offset:37920
	ds_write_b16_d16_hi v208, v191 offset:38448
	ds_write_b16 v208, v192 offset:38976
	ds_write_b16_d16_hi v208, v192 offset:39504
	ds_write_b16 v208, v193 offset:40032
	ds_write_b16_d16_hi v208, v193 offset:40560
	v_mad_u32_u24 v10, v144, s50, v12
	v_lshl_add_u32 v208, v144, 1, v13
	s_waitcnt vmcnt(3)
	ds_write_b128 v10, v[194:197]
	s_waitcnt vmcnt(2)
	ds_write_b16 v208, v198 offset:36864
	ds_write_b16_d16_hi v208, v198 offset:37392
	ds_write_b16 v208, v199 offset:37920
	ds_write_b16_d16_hi v208, v199 offset:38448
	ds_write_b16 v208, v200 offset:38976
	ds_write_b16_d16_hi v208, v200 offset:39504
	ds_write_b16 v208, v201 offset:40032
	ds_write_b16_d16_hi v208, v201 offset:40560
	s_branch .LBB0_764
